# DMA issue block moved to the top of each half-step (issued under the K-fragment LDS latency instead of between QK and PV)
# baseline (speedup 1.0000x reference)
.LBB0_398:
	ds_read_b128 v[222:225], v208 offset:40960
	ds_read_b128 v[226:229], v208 offset:45056
	v_exp_f32_e32 v148, v80
	v_exp_f32_e32 v149, v81
	s_cmpk_lt_u32 s51, 0x100
	s_cselect_b32 s0, s38, s34
	s_add_i32 s3, s0, s51
	s_mul_i32 s0, s3, 0x1800
	s_mul_hi_i32 s1, s3, 0x1800
	s_add_u32 s0, s39, s0
	s_addc_u32 s1, s42, s1
	s_max_i32 vcc_lo, s100, 0
	s_add_i32 vcc_lo, vcc_lo, s96
	s_add_i32 m0, vcc_lo, 0x4100
	s_nop 0
	global_load_lds_dwordx4 v129, s[0:1]
	s_add_i32 m0, vcc_lo, 0x4500
	s_nop 0
	global_load_lds_dwordx4 v130, s[0:1]
	s_mul_i32 s0, s3, 0x1800
	s_mul_hi_i32 s1, s3, 0x1800
	s_add_u32 s0, s28, s0
	s_addc_u32 s1, s29, s1
	s_max_i32 vcc_lo, s101, 0
	s_add_i32 vcc_lo, vcc_lo, s97
	s_add_i32 m0, vcc_lo, 0xa100
	s_nop 0
	global_load_lds_dwordx4 v128, s[0:1]
	s_waitcnt lgkmcnt(1)
	v_mfma_f32_32x32x16_bf16 v[112:127], v[222:225], v[64:67], v[96:111]
	ds_read_b128 v[230:233], v209 offset:40960
	ds_read_b128 v[182:185], v209 offset:45056
	ds_read_b128 v[150:153], v210 offset:40960
	v_exp_f32_e32 v154, v84
	v_exp_f32_e32 v155, v85
	v_exp_f32_e32 v158, v86
	v_exp_f32_e32 v159, v87
	v_exp_f32_e32 v156, v90
	v_exp_f32_e32 v157, v91
	s_waitcnt lgkmcnt(2)
	v_mfma_f32_32x32x16_bf16 v[112:127], v[230:233], v[68:71], v[112:127]
	ds_read_b128 v[234:237], v210 offset:45056
	ds_read_b128 v[218:221], v211 offset:45056
	ds_read_b128 v[160:163], v211 offset:40960
	v_exp_f32_e32 v166, v94
	v_exp_f32_e32 v167, v95
	s_waitcnt lgkmcnt(3)
	v_mfma_f32_32x32x16_bf16 v[112:127], v[150:153], v[72:75], v[112:127]
	v_exp_f32_e32 v152, v82
	v_exp_f32_e32 v153, v83
	v_exp_f32_e32 v150, v88
	v_exp_f32_e32 v151, v89
	s_waitcnt lgkmcnt(0)
	v_mfma_f32_32x32x16_bf16 v[112:127], v[160:163], v[76:79], v[112:127]
	v_exp_f32_e32 v162, v92
	v_exp_f32_e32 v163, v93
	v_mfma_f32_32x32x16_bf16 v[80:95], v[226:229], v[64:67], v[96:111]
	v_add_f32_e32 v238, v164, v148
	v_add_f32_e32 v238, v149, v238
	v_add_f32_e32 v238, v152, v238
	v_add_f32_e32 v238, v153, v238
	v_add_f32_e32 v238, v154, v238
	v_add_f32_e32 v238, v155, v238
	v_add_f32_e32 v238, v158, v238
	v_mfma_f32_32x32x16_bf16 v[80:95], v[182:185], v[68:71], v[80:95]
	v_add_f32_e32 v238, v159, v238
	v_add_f32_e32 v238, v150, v238
	v_add_f32_e32 v238, v151, v238
	v_add_f32_e32 v238, v156, v238
	v_add_f32_e32 v238, v157, v238
	v_add_f32_e32 v238, v162, v238
	v_add_f32_e32 v238, v163, v238
	v_mfma_f32_32x32x16_bf16 v[80:95], v[234:237], v[72:75], v[80:95]
	v_add_f32_e32 v239, v166, v238
	v_add_f32_e32 v239, v167, v239
	v_mov_b32_e32 v240, v239
	s_nop 1
	v_permlane32_swap_b32_e32 v239, v240
	v_add_f32_e32 v164, v239, v240
	v_cmp_ge_f32_e32 vcc, s99, v164
	v_mfma_f32_32x32x16_bf16 v[80:95], v[218:221], v[76:79], v[80:95]
	s_cmp_eq_u64 vcc, exec
	s_cbranch_scc0 .LBB0_405
.LBB0_400:
	v_cvt_pk_bf16_f32 v182, v148, v149
	v_cvt_pk_bf16_f32 v183, v152, v153
	v_cvt_pk_bf16_f32 v184, v154, v155
	v_cvt_pk_bf16_f32 v185, v158, v159
	v_cvt_pk_bf16_f32 v160, v150, v151
	v_cvt_pk_bf16_f32 v161, v156, v157
	v_cvt_pk_bf16_f32 v162, v162, v163
	v_cvt_pk_bf16_f32 v163, v166, v167
	ds_read_b64_tr_b16 v[186:187], v203 offset:0
	ds_read_b64_tr_b16 v[188:189], v203 offset:0x800
	ds_read_b64_tr_b16 v[214:215], v203 offset:0x200
	ds_read_b64_tr_b16 v[216:217], v203 offset:0xa00
	ds_read_b64_tr_b16 v[218:219], v203 offset:0x400
	ds_read_b64_tr_b16 v[220:221], v203 offset:0xc00
	ds_read_b64_tr_b16 v[222:223], v203 offset:0x600
	ds_read_b64_tr_b16 v[224:225], v203 offset:0xe00
	ds_read_b64_tr_b16 v[226:227], v203 offset:0x1000
	ds_read_b64_tr_b16 v[228:229], v203 offset:0x1800
	ds_read_b64_tr_b16 v[230:231], v203 offset:0x1200
	ds_read_b64_tr_b16 v[232:233], v203 offset:0x1a00
	ds_read_b64_tr_b16 v[234:235], v203 offset:0x1400
	ds_read_b64_tr_b16 v[236:237], v203 offset:0x1c00
	ds_read_b64_tr_b16 v[238:239], v203 offset:0x1600
	ds_read_b64_tr_b16 v[240:241], v203 offset:0x1e00
	s_nop 0
	s_waitcnt lgkmcnt(8)
	v_exp_f32_e32 v112, v112
	v_mfma_f32_32x32x16_bf16 v[0:15], v[144:147], v[186:189], v[0:15]
	v_exp_f32_e32 v113, v113
	v_exp_f32_e32 v114, v114
	v_exp_f32_e32 v115, v115
	v_exp_f32_e32 v116, v116
	v_exp_f32_e32 v117, v117
	v_exp_f32_e32 v118, v118
	v_exp_f32_e32 v119, v119
	v_mfma_f32_32x32x16_bf16 v[48:63], v[144:147], v[214:217], v[48:63]
	v_exp_f32_e32 v120, v120
	v_exp_f32_e32 v121, v121
	v_exp_f32_e32 v122, v122
	v_exp_f32_e32 v123, v123
	v_exp_f32_e32 v124, v124
	v_exp_f32_e32 v125, v125
	v_exp_f32_e32 v126, v126
	v_mfma_f32_32x32x16_bf16 v[32:47], v[144:147], v[218:221], v[32:47]
	v_exp_f32_e32 v127, v127
	v_mfma_f32_32x32x16_bf16 v[16:31], v[144:147], v[222:225], v[16:31]
	ds_read_b64_tr_b16 v[144:145], v203 offset:0x2000
	ds_read_b64_tr_b16 v[146:147], v203 offset:0x2800
	ds_read_b64_tr_b16 v[186:187], v203 offset:0x2200
	ds_read_b64_tr_b16 v[188:189], v203 offset:0x2a00
	ds_read_b64_tr_b16 v[214:215], v203 offset:0x2400
	ds_read_b64_tr_b16 v[216:217], v203 offset:0x2c00
	ds_read_b64_tr_b16 v[218:219], v203 offset:0x2600
	ds_read_b64_tr_b16 v[220:221], v203 offset:0x2e00
	s_waitcnt lgkmcnt(8)
	ds_read_b64_tr_b16 v[222:223], v203 offset:0x3000
	ds_read_b64_tr_b16 v[224:225], v203 offset:0x3800
	s_nop 0
	v_mfma_f32_32x32x16_bf16 v[0:15], v[140:143], v[226:229], v[0:15]
	ds_read_b64_tr_b16 v[226:227], v203 offset:0x3200
	ds_read_b64_tr_b16 v[228:229], v203 offset:0x3a00
	v_mfma_f32_32x32x16_bf16 v[48:63], v[140:143], v[230:233], v[48:63]
	ds_read_b64_tr_b16 v[230:231], v203 offset:0x3400
	ds_read_b64_tr_b16 v[232:233], v203 offset:0x3c00
	v_mfma_f32_32x32x16_bf16 v[32:47], v[140:143], v[234:237], v[32:47]
	ds_read_b64_tr_b16 v[234:235], v203 offset:0x3600
	ds_read_b64_tr_b16 v[236:237], v203 offset:0x3e00
	s_waitcnt lgkmcnt(8)
	s_nop 0
	s_waitcnt lgkmcnt(0)
	v_mfma_f32_32x32x16_bf16 v[16:31], v[140:143], v[238:241], v[16:31]
	v_add_f32_e32 v140, 0, v112
	v_add_f32_e32 v140, v113, v140
	v_add_f32_e32 v140, v114, v140
	v_add_f32_e32 v140, v115, v140
	v_add_f32_e32 v140, v116, v140
	v_add_f32_e32 v140, v117, v140
	v_add_f32_e32 v140, v118, v140
	v_mfma_f32_32x32x16_bf16 v[0:15], v[182:185], v[144:147], v[0:15]
	v_add_f32_e32 v140, v119, v140
	v_add_f32_e32 v140, v120, v140
	v_add_f32_e32 v140, v121, v140
	v_add_f32_e32 v140, v122, v140
	v_add_f32_e32 v140, v123, v140
	v_add_f32_e32 v140, v124, v140
	v_add_f32_e32 v140, v125, v140
	v_mfma_f32_32x32x16_bf16 v[48:63], v[182:185], v[186:189], v[48:63]
	v_add_f32_e32 v140, v126, v140
	v_add_f32_e32 v165, v127, v140
	v_cvt_pk_bf16_f32 v144, v112, v113
	v_cvt_pk_bf16_f32 v145, v114, v115
	v_cvt_pk_bf16_f32 v146, v116, v117
	v_cvt_pk_bf16_f32 v147, v118, v119
	v_cvt_pk_bf16_f32 v140, v120, v121
	v_mfma_f32_32x32x16_bf16 v[32:47], v[182:185], v[214:217], v[32:47]
	v_cvt_pk_bf16_f32 v141, v122, v123
	v_cvt_pk_bf16_f32 v142, v124, v125
	v_cvt_pk_bf16_f32 v143, v126, v127
	v_mfma_f32_32x32x16_bf16 v[16:31], v[182:185], v[218:221], v[16:31]
	s_waitcnt vmcnt(3)
	s_waitcnt lgkmcnt(0)
	s_barrier
	v_mfma_f32_32x32x16_bf16 v[0:15], v[160:163], v[222:225], v[0:15]
	v_mfma_f32_32x32x16_bf16 v[48:63], v[160:163], v[226:229], v[48:63]
	v_mfma_f32_32x32x16_bf16 v[32:47], v[160:163], v[230:233], v[32:47]
	v_mfma_f32_32x32x16_bf16 v[16:31], v[160:163], v[234:237], v[16:31]
	v_add_u32_e32 v208, s101, v208
	v_add_u32_e32 v209, s101, v209
	v_add_u32_e32 v210, s101, v210
	v_add_u32_e32 v211, s101, v211
	ds_read_b128 v[160:163], v208 offset:32768
	ds_read_b128 v[222:225], v208 offset:36864
	v_exp_f32_e32 v166, v84
	v_exp_f32_e32 v167, v85
	s_cmp_ge_u32 s50, s35
	s_cbranch_scc1 .Ldma_skip2
	s_add_i32 s0, s34, s51
	s_add_i32 s3, s0, 64
	s_mul_i32 s0, s3, 0x1800
	s_mul_hi_i32 s1, s3, 0x1800
	s_add_u32 s0, s39, s0
	s_addc_u32 s1, s42, s1
	s_sub_i32 vcc_lo, 0, s100
	s_max_i32 vcc_lo, vcc_lo, 0
	s_add_i32 vcc_lo, vcc_lo, s96
	s_add_i32 m0, vcc_lo, 0x100
	s_nop 0
	global_load_lds_dwordx4 v129, s[0:1]
	s_add_i32 m0, vcc_lo, 0x500
	s_nop 0
	global_load_lds_dwordx4 v130, s[0:1]
	s_mul_i32 s0, s3, 0x1800
	s_mul_hi_i32 s1, s3, 0x1800
	s_add_u32 s0, s28, s0
	s_addc_u32 s1, s29, s1
	s_sub_i32 vcc_lo, 0, s101
	s_max_i32 vcc_lo, vcc_lo, 0
	s_add_i32 vcc_lo, vcc_lo, s97
	s_add_i32 m0, vcc_lo, 0x8100
	s_nop 0
	global_load_lds_dwordx4 v128, s[0:1]
.Ldma_skip2:
	s_waitcnt lgkmcnt(1)
	v_mfma_f32_32x32x16_bf16 v[112:127], v[160:163], v[64:67], v[96:111]
	ds_read_b128 v[160:163], v209 offset:32768
	ds_read_b128 v[226:229], v209 offset:36864
	ds_read_b128 v[238:241], v210 offset:36864
	ds_read_b128 v[182:185], v210 offset:32768
	ds_read_b128 v[242:245], v211 offset:36864
	ds_read_b128 v[188:191], v211 offset:32768
	v_exp_f32_e32 v186, v90
	v_exp_f32_e32 v187, v91
	s_andn2_b64 s[0:1], s[6:7], exec
	s_and_b64 s[6:7], s[8:9], exec
	s_or_b64 s[6:7], s[0:1], s[6:7]
	s_waitcnt lgkmcnt(5)
	v_mfma_f32_32x32x16_bf16 v[112:127], v[160:163], v[68:71], v[112:127]
	v_exp_f32_e32 v160, v80
	v_exp_f32_e32 v161, v81
	v_exp_f32_e32 v162, v82
	v_exp_f32_e32 v163, v83
	v_add_f32_e32 v80, v160, v165
	v_add_f32_e32 v80, v161, v80
	v_add_f32_e32 v165, v162, v80
	s_waitcnt lgkmcnt(2)
	v_mfma_f32_32x32x16_bf16 v[112:127], v[182:185], v[72:75], v[112:127]
	v_exp_f32_e32 v182, v86
	v_exp_f32_e32 v183, v87
	v_exp_f32_e32 v184, v88
	v_exp_f32_e32 v185, v89
	v_add_f32_e32 v165, v163, v165
	v_add_f32_e32 v165, v166, v165
	v_add_f32_e32 v165, v167, v165
	s_waitcnt lgkmcnt(0)
	v_mfma_f32_32x32x16_bf16 v[112:127], v[188:191], v[76:79], v[112:127]
	v_exp_f32_e32 v188, v92
	v_exp_f32_e32 v189, v93
	v_exp_f32_e32 v190, v94
	v_exp_f32_e32 v191, v95
	v_add_f32_e32 v165, v182, v165
	v_add_f32_e32 v165, v183, v165
	v_add_f32_e32 v165, v184, v165
	v_mfma_f32_32x32x16_bf16 v[80:95], v[222:225], v[64:67], v[96:111]
	v_add_f32_e32 v165, v185, v165
	v_add_f32_e32 v165, v186, v165
	v_add_f32_e32 v165, v187, v165
	v_add_f32_e32 v165, v188, v165
	v_add_f32_e32 v165, v189, v165
	v_add_f32_e32 v165, v190, v165
	v_add_f32_e32 v165, v191, v165
	v_mfma_f32_32x32x16_bf16 v[80:95], v[226:229], v[68:71], v[80:95]
	v_mov_b32_e32 v179, v165
	s_nop 1
	v_permlane32_swap_b32_e32 v165, v179
	v_add_f32_e64 v178, v164, v178
	v_add_f32_e64 v179, v165, v179
	v_cmp_ge_f32_e32 vcc, s99, v179
	s_cmp_eq_u64 vcc, exec
	v_mfma_f32_32x32x16_bf16 v[80:95], v[238:241], v[72:75], v[80:95]
	v_mfma_f32_32x32x16_bf16 v[80:95], v[242:245], v[76:79], v[80:95]
	s_cbranch_scc0 .LBB0_408
.LBB0_401:
	v_cvt_pk_bf16_f32 v164, v160, v161
	v_cvt_pk_bf16_f32 v165, v162, v163
	v_cvt_pk_bf16_f32 v166, v166, v167
	v_cvt_pk_bf16_f32 v167, v182, v183
	v_cvt_pk_bf16_f32 v160, v184, v185
	v_cvt_pk_bf16_f32 v161, v186, v187
	v_cvt_pk_bf16_f32 v162, v188, v189
	v_cvt_pk_bf16_f32 v163, v190, v191
	s_cmp_ge_u32 s50, s35
	s_cselect_b64 s[8:9], -1, 0
	s_and_b64 vcc, exec, s[8:9]
	s_cbranch_vccnz .LBB0_403
.LBB0_403:
	v_add_f32_e32 v178, v179, v178
	ds_read_b64_tr_b16 v[182:183], v202 offset:0
	ds_read_b64_tr_b16 v[184:185], v202 offset:0x800
	ds_read_b64_tr_b16 v[186:187], v202 offset:0x200
	ds_read_b64_tr_b16 v[188:189], v202 offset:0xa00
	ds_read_b64_tr_b16 v[214:215], v202 offset:0x400
	ds_read_b64_tr_b16 v[216:217], v202 offset:0xc00
	ds_read_b64_tr_b16 v[218:219], v202 offset:0x600
	ds_read_b64_tr_b16 v[220:221], v202 offset:0xe00
	ds_read_b64_tr_b16 v[222:223], v202 offset:0x1000
	ds_read_b64_tr_b16 v[224:225], v202 offset:0x1800
	ds_read_b64_tr_b16 v[226:227], v202 offset:0x1200
	ds_read_b64_tr_b16 v[228:229], v202 offset:0x1a00
	ds_read_b64_tr_b16 v[230:231], v202 offset:0x1400
	ds_read_b64_tr_b16 v[232:233], v202 offset:0x1c00
	ds_read_b64_tr_b16 v[234:235], v202 offset:0x1600
	ds_read_b64_tr_b16 v[236:237], v202 offset:0x1e00
	s_nop 0
	s_waitcnt lgkmcnt(8)
	v_exp_f32_e32 v112, v112
	v_mfma_f32_32x32x16_bf16 v[0:15], v[144:147], v[182:185], v[0:15]
	v_exp_f32_e32 v113, v113
	v_exp_f32_e32 v114, v114
	v_exp_f32_e32 v115, v115
	v_exp_f32_e32 v116, v116
	v_exp_f32_e32 v117, v117
	v_exp_f32_e32 v118, v118
	v_exp_f32_e32 v119, v119
	v_mfma_f32_32x32x16_bf16 v[48:63], v[144:147], v[186:189], v[48:63]
	v_exp_f32_e32 v120, v120
	v_exp_f32_e32 v121, v121
	v_exp_f32_e32 v122, v122
	v_exp_f32_e32 v123, v123
	v_exp_f32_e32 v124, v124
	v_exp_f32_e32 v125, v125
	v_exp_f32_e32 v126, v126
	v_mfma_f32_32x32x16_bf16 v[32:47], v[144:147], v[214:217], v[32:47]
	v_exp_f32_e32 v127, v127
	s_addk_i32 s51, 0x80
	s_add_i32 s50, s50, 2
	s_and_b64 vcc, exec, s[8:9]
	v_mfma_f32_32x32x16_bf16 v[16:31], v[144:147], v[218:221], v[16:31]
	ds_read_b64_tr_b16 v[144:145], v202 offset:0x2000
	ds_read_b64_tr_b16 v[146:147], v202 offset:0x2800
	ds_read_b64_tr_b16 v[182:183], v202 offset:0x2200
	ds_read_b64_tr_b16 v[184:185], v202 offset:0x2a00
	ds_read_b64_tr_b16 v[186:187], v202 offset:0x2400
	ds_read_b64_tr_b16 v[188:189], v202 offset:0x2c00
	ds_read_b64_tr_b16 v[214:215], v202 offset:0x2600
	ds_read_b64_tr_b16 v[216:217], v202 offset:0x2e00
	s_waitcnt lgkmcnt(8)
	ds_read_b64_tr_b16 v[218:219], v202 offset:0x3000
	ds_read_b64_tr_b16 v[220:221], v202 offset:0x3800
	s_nop 0
	v_mfma_f32_32x32x16_bf16 v[0:15], v[140:143], v[222:225], v[0:15]
	ds_read_b64_tr_b16 v[222:223], v202 offset:0x3200
	ds_read_b64_tr_b16 v[224:225], v202 offset:0x3a00
	v_mfma_f32_32x32x16_bf16 v[48:63], v[140:143], v[226:229], v[48:63]
	ds_read_b64_tr_b16 v[226:227], v202 offset:0x3400
	ds_read_b64_tr_b16 v[228:229], v202 offset:0x3c00
	v_mfma_f32_32x32x16_bf16 v[32:47], v[140:143], v[230:233], v[32:47]
	ds_read_b64_tr_b16 v[230:231], v202 offset:0x3600
	ds_read_b64_tr_b16 v[232:233], v202 offset:0x3e00
	s_waitcnt lgkmcnt(8)
	s_nop 0
	s_waitcnt lgkmcnt(0)
	v_mfma_f32_32x32x16_bf16 v[16:31], v[140:143], v[234:237], v[16:31]
	v_add_f32_e32 v140, 0, v112
	v_add_f32_e32 v140, v113, v140
	v_add_f32_e32 v140, v114, v140
	v_add_f32_e32 v140, v115, v140
	v_add_f32_e32 v140, v116, v140
	v_add_f32_e32 v140, v117, v140
	v_add_f32_e32 v140, v118, v140
	v_mfma_f32_32x32x16_bf16 v[0:15], v[164:167], v[144:147], v[0:15]
	v_add_f32_e32 v140, v119, v140
	v_add_f32_e32 v140, v120, v140
	v_add_f32_e32 v140, v121, v140
	v_add_f32_e32 v140, v122, v140
	v_add_f32_e32 v140, v123, v140
	v_add_f32_e32 v140, v124, v140
	v_add_f32_e32 v140, v125, v140
	v_mfma_f32_32x32x16_bf16 v[48:63], v[164:167], v[182:185], v[48:63]
	v_add_f32_e32 v140, v126, v140
	v_cvt_pk_bf16_f32 v144, v112, v113
	v_cvt_pk_bf16_f32 v145, v114, v115
	v_cvt_pk_bf16_f32 v146, v116, v117
	v_cvt_pk_bf16_f32 v147, v118, v119
	v_mfma_f32_32x32x16_bf16 v[32:47], v[164:167], v[186:189], v[32:47]
	v_mfma_f32_32x32x16_bf16 v[16:31], v[164:167], v[214:217], v[16:31]
	v_add_f32_e32 v164, v127, v140
	v_cvt_pk_bf16_f32 v140, v120, v121
	v_cvt_pk_bf16_f32 v141, v122, v123
	v_cvt_pk_bf16_f32 v142, v124, v125
	v_cvt_pk_bf16_f32 v143, v126, v127
	v_mfma_f32_32x32x16_bf16 v[0:15], v[160:163], v[218:221], v[0:15]
	s_waitcnt vmcnt(3)
	s_cbranch_vccz .Ldma_w3
	s_waitcnt vmcnt(0)
